# residual-add GEMM epilogues: counted vmcnt waits per consumer group instead of vmcnt(0) (out-proj, FFN-down first halves); FFN-down second half no longer drains VMEM before issuing its residual loads
# baseline (speedup 1.0000x reference)
;     __device__ __forceinline__ void operator()(const f32x4 (&acc)[2][2][4][2], const Unit& u, int wr, int wc, int fr, int fq) const {
;     ...
;         const int col0 = u.pn * BM + wc * 32 + 8 * fq;
;         const int rt = u.pm * BM; const float* bb = (rt < split) ? b0 + (size_t)rt * 2048 : b1 + (size_t)(rt - split) * 2048; float* oo = out + (size_t)rt * 2048; bf16_t* xx = xn + (size_t)rt * 2048;
;         float sacc[2][4];
;         f32x4 gv[2][2];
; #pragma unroll
;         for (int bj = 0; bj < 2; ++bj) { gv[bj][0] = *(const f32x4*)(g + col0 + bj * HALF); gv[bj][1] = *(const f32x4*)(g + col0 + bj * HALF + 4); }
; #pragma unroll
;         for (int ai = 0; ai < 2; ++ai) {
;             f32x4 pre[4][2][2]; float rq[4];
; #pragma unroll
;             for (int m = 0; m < 4; ++m) { const size_t off = (size_t)(ai * HALF + wr * 64 + m * 16 + fr) * 2048 + col0; rq[m] = rs2 ? rs2[rt + ai * HALF + wr * 64 + m * 16 + fr] : 0.f;
; #pragma unroll
;                 for (int bj = 0; bj < 2; ++bj) { pre[m][bj][0] = *(const f32x4*)(bb + off + bj * HALF); pre[m][bj][1] = *(const f32x4*)(bb + off + bj * HALF + 4); } }
;             asm volatile("" ::: "memory");
; #pragma unroll
;             for (int m = 0; m < 4; ++m) { const int rl = ai * HALF + wr * 64 + m * 16 + fr; const size_t off = (size_t)rl * 2048 + col0; float s = 0.f; const float sc = rs2 ? __builtin_amdgcn_rcpf(rq[m] * (1.f / 2048.f) + 1e-6f) : 1.f;
; #pragma unroll
;                 for (int bj = 0; bj < 2; ++bj) {
;                     const f32x4 v0 = pre[m][bj][0] + acc[ai][bj][m][0] * sc, v1 = pre[m][bj][1] + acc[ai][bj][m][1] * sc;
;                     __builtin_nontemporal_store(v0, (f32x4*)(oo + off + bj * HALF)); __builtin_nontemporal_store(v1, (f32x4*)(oo + off + bj * HALF + 4));
;                     s += (v0[0] * v0[0] + v0[1] * v0[1]) + (v0[2] * v0[2] + v0[3] * v0[3]) + (v1[0] * v1[0] + v1[1] * v1[1]) + (v1[2] * v1[2] + v1[3] * v1[3]);
;                     const f32x4 a = v0 * gv[bj][0], b = v1 * gv[bj][1];
;                     u32x4 w; w.x = cvt_pk_bf16(a[0], a[1]); w.y = cvt_pk_bf16(a[2], a[3]); w.z = cvt_pk_bf16(b[0], b[1]); w.w = cvt_pk_bf16(b[2], b[3]);
;                     if (xn) *(u32x4*)(xx + off + bj * HALF) = w; }
;                 s += __shfl_xor(s, 16); s += __shfl_xor(s, 32); sacc[ai][m] = s; }
.LBB0_318:
	s_lshl_b32 s34, s92, 8
	s_or_b32 s34, s34, s88
	v_lshl_add_u32 v222, v221, 3, s34
	v_ashrrev_i32_e32 v223, 31, v222
	v_add_u32_e32 v226, s96, v220
	v_lshlrev_b64 v[144:145], 2, v[222:223]
	v_ashrrev_i32_e32 v227, 31, v226
	v_lshl_add_u64 v[68:69], s[42:43], 0, v[144:145]
	v_lshl_add_u64 v[224:225], s[6:7], 0, v[144:145]
	v_lshlrev_b64 v[144:145], 13, v[226:227]
	v_add_u32_e32 v232, 16, v226
	v_lshl_add_u64 v[144:145], v[224:225], 0, v[144:145]
	v_ashrrev_i32_e32 v233, 31, v232
	global_load_dwordx4 v[72:75], v[68:69], off offset:16
	global_load_dwordx4 v[76:79], v[68:69], off
	global_load_dwordx4 v[64:67], v[68:69], off offset:528
	s_nop 0
	global_load_dwordx4 v[68:71], v[68:69], off offset:512
	s_nop 0
	global_load_dwordx4 v[200:203], v[144:145], off offset:16
	global_load_dwordx4 v[206:209], v[144:145], off
	global_load_dwordx4 v[192:195], v[144:145], off offset:528
	global_load_dwordx4 v[196:199], v[144:145], off offset:512
	v_lshlrev_b64 v[144:145], 13, v[232:233]
	v_add_u32_e32 v230, 32, v226
	v_lshl_add_u64 v[144:145], v[224:225], 0, v[144:145]
	v_ashrrev_i32_e32 v231, 31, v230
	global_load_dwordx4 v[184:187], v[144:145], off offset:16
	global_load_dwordx4 v[188:191], v[144:145], off
	global_load_dwordx4 v[176:179], v[144:145], off offset:528
	global_load_dwordx4 v[180:183], v[144:145], off offset:512
	v_lshlrev_b64 v[144:145], 13, v[230:231]
	v_add_u32_e32 v228, 48, v226
	v_lshl_add_u64 v[144:145], v[224:225], 0, v[144:145]
	v_ashrrev_i32_e32 v229, 31, v228
	global_load_dwordx4 v[168:171], v[144:145], off offset:16
	global_load_dwordx4 v[172:175], v[144:145], off
	global_load_dwordx4 v[160:163], v[144:145], off offset:528
	global_load_dwordx4 v[164:167], v[144:145], off offset:512
	v_lshlrev_b64 v[144:145], 13, v[228:229]
	v_lshl_add_u64 v[148:149], v[224:225], 0, v[144:145]
	global_load_dwordx4 v[152:155], v[148:149], off offset:16
	global_load_dwordx4 v[156:159], v[148:149], off
	global_load_dwordx4 v[144:147], v[148:149], off offset:528
	s_nop 0
	global_load_dwordx4 v[148:151], v[148:149], off offset:512
	s_lshl_b64 s[6:7], s[62:63], 13
	s_add_u32 s92, s28, s6
	s_addc_u32 s93, s29, s7
	s_lshl_b64 s[6:7], s[62:63], 12
	v_lshlrev_b64 v[234:235], 11, v[226:227]
	s_add_u32 s98, s58, s6
	v_lshl_add_u64 v[236:237], v[234:235], 0, v[222:223]
	s_addc_u32 s99, s59, s7
	v_lshl_add_u64 v[234:235], v[236:237], 2, s[92:93]
	s_and_b64 vcc, exec, s[46:47]
	v_lshl_add_u64 v[236:237], v[236:237], 1, s[98:99]
	s_waitcnt vmcnt(14)
	v_pk_add_f32 v[138:139], v[138:139], v[202:203]
	v_pk_add_f32 v[142:143], v[142:143], v[208:209]
	v_pk_add_f32 v[140:141], v[140:141], v[206:207]
	v_pk_add_f32 v[136:137], v[136:137], v[200:201]
	v_pk_mul_f32 v[202:203], v[78:79], v[142:143]
	v_pk_mul_f32 v[200:201], v[76:77], v[140:141]
	global_store_dwordx4 v[234:235], v[140:143], off nt
	global_store_dwordx4 v[234:235], v[136:139], off offset:16 nt
	v_pk_mul_f32 v[206:207], v[74:75], v[138:139]
	v_pk_mul_f32 v[208:209], v[72:73], v[136:137]
	v_cvt_pk_bf16_f32 v200, v200, v201
	v_cvt_pk_bf16_f32 v201, v202, v203
	s_nop 0
	v_cvt_pk_bf16_f32 v202, v208, v209
	v_cvt_pk_bf16_f32 v203, v206, v207
	s_cbranch_vccz .LBB0_320
	global_store_dwordx4 v[236:237], v[200:203], off
.LBB0_320:
	s_waitcnt vmcnt(14)
	v_pk_add_f32 v[134:135], v[134:135], v[198:199]
	v_pk_add_f32 v[132:133], v[132:133], v[196:197]
	v_pk_add_f32 v[130:131], v[130:131], v[194:195]
	v_pk_add_f32 v[128:129], v[128:129], v[192:193]
	v_pk_mul_f32 v[194:195], v[70:71], v[134:135]
	v_pk_mul_f32 v[192:193], v[68:69], v[132:133]
	global_store_dwordx4 v[234:235], v[132:135], off offset:512 nt
	global_store_dwordx4 v[234:235], v[128:131], off offset:528 nt
	v_cvt_pk_bf16_f32 v192, v192, v193
	v_cvt_pk_bf16_f32 v193, v194, v195
	v_cndmask_b32_e64 v195, 0, 1, s[46:47]
	v_cmp_ne_u32_e64 s[6:7], 1, v195
	s_andn2_b64 vcc, exec, s[46:47]
	v_pk_mul_f32 v[196:197], v[66:67], v[130:131]
	v_pk_mul_f32 v[198:199], v[64:65], v[128:129]
	s_nop 0
	v_cvt_pk_bf16_f32 v194, v198, v199
	v_cvt_pk_bf16_f32 v195, v196, v197
	s_cbranch_vccnz .LBB0_322
	global_store_dwordx4 v[236:237], v[192:195], off offset:256
.LBB0_322:
	v_mul_f32_e32 v133, v133, v133
	v_fmac_f32_e32 v133, v132, v132
	v_mul_f32_e32 v132, v135, v135
	v_mul_f32_e32 v141, v141, v141
	v_fmac_f32_e32 v132, v134, v134
	v_mul_f32_e32 v129, v129, v129
	v_fmac_f32_e32 v141, v140, v140
	v_mul_f32_e32 v140, v143, v143
	v_add_f32_e32 v132, v133, v132
	v_fmac_f32_e32 v129, v128, v128
	v_fmac_f32_e32 v140, v142, v142
	v_mul_f32_e32 v137, v137, v137
	v_add_f32_e32 v128, v132, v129
	v_mul_f32_e32 v129, v131, v131
	v_add_f32_e32 v140, v141, v140
	v_fmac_f32_e32 v137, v136, v136
	v_fmac_f32_e32 v129, v130, v130
	v_and_b32_e32 v130, 64, v247
	v_add_f32_e32 v136, v137, v140
	v_mul_f32_e32 v137, v139, v139
	v_add_f32_e32 v128, v129, v128
	v_xor_b32_e32 v129, 16, v247
	v_add_u32_e32 v130, 64, v130
	v_fmac_f32_e32 v137, v138, v138
	v_cmp_lt_i32_e32 vcc, v129, v130
	v_add_f32_e32 v136, v137, v136
	v_add_f32_e32 v128, v136, v128
	v_cndmask_b32_e32 v129, v247, v129, vcc
	v_lshlrev_b32_e32 v194, 2, v129
	ds_bpermute_b32 v129, v194, v128
	s_waitcnt vmcnt(14)
	v_pk_add_f32 v[126:127], v[126:127], v[190:191]
	v_pk_add_f32 v[124:125], v[124:125], v[188:189]
	v_pk_add_f32 v[122:123], v[122:123], v[186:187]
	v_pk_add_f32 v[120:121], v[120:121], v[184:185]
	s_waitcnt lgkmcnt(0)
	v_add_f32_e32 v192, v128, v129
	v_xor_b32_e32 v128, 32, v247
	v_cmp_lt_i32_e32 vcc, v128, v130
	v_pk_mul_f32 v[130:131], v[78:79], v[126:127]
	v_pk_mul_f32 v[136:137], v[74:75], v[122:123]
	v_cndmask_b32_e32 v128, v247, v128, vcc
	v_lshlrev_b32_e32 v195, 2, v128
	ds_bpermute_b32 v193, v195, v192
	v_lshlrev_b64 v[128:129], 11, v[232:233]
	v_lshl_add_u64 v[128:129], v[128:129], 0, v[222:223]
	v_lshl_add_u64 v[134:135], v[128:129], 2, s[92:93]
	v_lshl_add_u64 v[132:133], v[128:129], 1, s[98:99]
	v_pk_mul_f32 v[128:129], v[76:77], v[124:125]
	s_and_b64 vcc, exec, s[6:7]
	global_store_dwordx4 v[134:135], v[124:127], off nt
	global_store_dwordx4 v[134:135], v[120:123], off offset:16 nt
	v_pk_mul_f32 v[138:139], v[72:73], v[120:121]
	v_cvt_pk_bf16_f32 v128, v128, v129
	v_cvt_pk_bf16_f32 v129, v130, v131
	s_nop 0
	v_cvt_pk_bf16_f32 v130, v138, v139
	v_cvt_pk_bf16_f32 v131, v136, v137
	s_cbranch_vccnz .LBB0_324
	global_store_dwordx4 v[132:133], v[128:131], off
; __device__ __forceinline__ unsigned cvt_pk_bf16(float lo, float hi) { unsigned r; asm volatile("v_cvt_pk_bf16_f32 %0, %1, %2" : "=v"(r) : "v"(lo), "v"(hi)); return r; }
;     __device__ __forceinline__ void operator()(const f32x4 (&acc)[2][2][4][2], const Unit& u, int wr, int wc, int fr, int fq) const {
;     ...
;             for (int m = 0; m < 4; ++m) { const int rl = ai * HALF + wr * 64 + m * 16 + fr; const size_t off = (size_t)rl * 2048 + col0; float s = 0.f; const float sc = rs2 ? __builtin_amdgcn_rcpf(rq[m] * (1.f / 2048.f) + 1e-6f) : 1.f;
; #pragma unroll
;                 for (int bj = 0; bj < 2; ++bj) {
;                     const f32x4 v0 = pre[m][bj][0] + acc[ai][bj][m][0] * sc, v1 = pre[m][bj][1] + acc[ai][bj][m][1] * sc;
;                     __builtin_nontemporal_store(v0, (f32x4*)(oo + off + bj * HALF)); __builtin_nontemporal_store(v1, (f32x4*)(oo + off + bj * HALF + 4));
;                     s += (v0[0] * v0[0] + v0[1] * v0[1]) + (v0[2] * v0[2] + v0[3] * v0[3]) + (v1[0] * v1[0] + v1[1] * v1[1]) + (v1[2] * v1[2] + v1[3] * v1[3]);
;                     const f32x4 a = v0 * gv[bj][0], b = v1 * gv[bj][1];
;                     u32x4 w; w.x = cvt_pk_bf16(a[0], a[1]); w.y = cvt_pk_bf16(a[2], a[3]); w.z = cvt_pk_bf16(b[0], b[1]); w.w = cvt_pk_bf16(b[2], b[3]);
;                     if (xn) *(u32x4*)(xx + off + bj * HALF) = w; }
;                 s += __shfl_xor(s, 16); s += __shfl_xor(s, 32); sacc[ai][m] = s; }
.LBB0_324:
	s_waitcnt vmcnt(14)
	v_pk_add_f32 v[118:119], v[118:119], v[182:183]
	v_pk_add_f32 v[116:117], v[116:117], v[180:181]
	v_pk_add_f32 v[114:115], v[114:115], v[178:179]
	v_pk_add_f32 v[112:113], v[112:113], v[176:177]
	v_pk_mul_f32 v[130:131], v[70:71], v[118:119]
	v_pk_mul_f32 v[128:129], v[68:69], v[116:117]
	s_and_b64 vcc, exec, s[6:7]
	global_store_dwordx4 v[134:135], v[116:119], off offset:512 nt
	global_store_dwordx4 v[134:135], v[112:115], off offset:528 nt
	v_pk_mul_f32 v[134:135], v[66:67], v[114:115]
	v_pk_mul_f32 v[136:137], v[64:65], v[112:113]
	v_cvt_pk_bf16_f32 v128, v128, v129
	v_cvt_pk_bf16_f32 v129, v130, v131
	s_nop 0
	v_cvt_pk_bf16_f32 v130, v136, v137
	v_cvt_pk_bf16_f32 v131, v134, v135
	s_cbranch_vccnz .LBB0_326
	global_store_dwordx4 v[132:133], v[128:131], off offset:256
.LBB0_326:
	v_mul_f32_e32 v125, v125, v125
	v_mul_f32_e32 v117, v117, v117
	v_fmac_f32_e32 v125, v124, v124
	v_mul_f32_e32 v124, v127, v127
	v_fmac_f32_e32 v117, v116, v116
	v_mul_f32_e32 v116, v119, v119
	v_fmac_f32_e32 v124, v126, v126
	v_mul_f32_e32 v121, v121, v121
	v_fmac_f32_e32 v116, v118, v118
	v_mul_f32_e32 v113, v113, v113
	v_add_f32_e32 v124, v125, v124
	v_fmac_f32_e32 v121, v120, v120
	v_add_f32_e32 v116, v117, v116
	v_fmac_f32_e32 v113, v112, v112
	v_add_f32_e32 v120, v121, v124
	v_mul_f32_e32 v121, v123, v123
	v_add_f32_e32 v112, v116, v113
	v_mul_f32_e32 v113, v115, v115
	v_fmac_f32_e32 v121, v122, v122
	v_fmac_f32_e32 v113, v114, v114
	v_add_f32_e32 v120, v121, v120
	v_add_f32_e32 v112, v113, v112
	v_add_f32_e32 v112, v120, v112
	ds_bpermute_b32 v113, v194, v112
	s_waitcnt vmcnt(14)
	v_pk_add_f32 v[110:111], v[110:111], v[174:175]
	v_pk_add_f32 v[108:109], v[108:109], v[172:173]
	v_pk_add_f32 v[106:107], v[106:107], v[170:171]
	v_pk_add_f32 v[104:105], v[104:105], v[168:169]
	s_waitcnt lgkmcnt(0)
	v_add_f32_e32 v176, v112, v113
	ds_bpermute_b32 v177, v195, v176
	v_lshlrev_b64 v[112:113], 11, v[230:231]
	v_lshl_add_u64 v[112:113], v[112:113], 0, v[222:223]
	v_lshl_add_u64 v[118:119], v[112:113], 2, s[92:93]
	v_lshl_add_u64 v[116:117], v[112:113], 1, s[98:99]
	v_pk_mul_f32 v[114:115], v[78:79], v[110:111]
	v_pk_mul_f32 v[112:113], v[76:77], v[108:109]
	s_and_b64 vcc, exec, s[6:7]
	global_store_dwordx4 v[118:119], v[108:111], off nt
	global_store_dwordx4 v[118:119], v[104:107], off offset:16 nt
	v_pk_mul_f32 v[120:121], v[74:75], v[106:107]
	v_pk_mul_f32 v[122:123], v[72:73], v[104:105]
	v_cvt_pk_bf16_f32 v112, v112, v113
	v_cvt_pk_bf16_f32 v113, v114, v115
	s_nop 0
	v_cvt_pk_bf16_f32 v114, v122, v123
	v_cvt_pk_bf16_f32 v115, v120, v121
	s_cbranch_vccnz .LBB0_328
	global_store_dwordx4 v[116:117], v[112:115], off
.LBB0_328:
	s_waitcnt vmcnt(14)
	v_pk_add_f32 v[102:103], v[102:103], v[166:167]
	v_pk_add_f32 v[100:101], v[100:101], v[164:165]
	v_pk_add_f32 v[98:99], v[98:99], v[162:163]
	v_pk_add_f32 v[96:97], v[96:97], v[160:161]
	v_pk_mul_f32 v[114:115], v[70:71], v[102:103]
	v_pk_mul_f32 v[112:113], v[68:69], v[100:101]
	s_and_b64 vcc, exec, s[6:7]
	global_store_dwordx4 v[118:119], v[100:103], off offset:512 nt
	global_store_dwordx4 v[118:119], v[96:99], off offset:528 nt
	v_pk_mul_f32 v[118:119], v[66:67], v[98:99]
	v_pk_mul_f32 v[120:121], v[64:65], v[96:97]
	v_cvt_pk_bf16_f32 v112, v112, v113
	v_cvt_pk_bf16_f32 v113, v114, v115
	s_nop 0
	v_cvt_pk_bf16_f32 v114, v120, v121
	v_cvt_pk_bf16_f32 v115, v118, v119
	s_cbranch_vccnz .LBB0_330
	global_store_dwordx4 v[116:117], v[112:115], off offset:256
.LBB0_330:
	v_mul_f32_e32 v109, v109, v109
	v_mul_f32_e32 v101, v101, v101
	v_fmac_f32_e32 v109, v108, v108
	v_mul_f32_e32 v108, v111, v111
	v_fmac_f32_e32 v101, v100, v100
	v_mul_f32_e32 v100, v103, v103
	v_fmac_f32_e32 v108, v110, v110
	v_mul_f32_e32 v105, v105, v105
	v_fmac_f32_e32 v100, v102, v102
	v_mul_f32_e32 v97, v97, v97
	v_add_f32_e32 v108, v109, v108
	v_fmac_f32_e32 v105, v104, v104
	v_add_f32_e32 v100, v101, v100
	v_fmac_f32_e32 v97, v96, v96
	v_add_f32_e32 v104, v105, v108
	v_mul_f32_e32 v105, v107, v107
	v_add_f32_e32 v96, v100, v97
	v_mul_f32_e32 v97, v99, v99
	v_fmac_f32_e32 v105, v106, v106
	v_fmac_f32_e32 v97, v98, v98
	v_add_f32_e32 v104, v105, v104
	v_add_f32_e32 v96, v97, v96
	v_add_f32_e32 v96, v104, v96
	ds_bpermute_b32 v97, v194, v96
	s_waitcnt vmcnt(14)
	v_pk_add_f32 v[94:95], v[94:95], v[158:159]
	v_pk_add_f32 v[92:93], v[92:93], v[156:157]
	v_pk_add_f32 v[90:91], v[90:91], v[154:155]
	v_pk_add_f32 v[88:89], v[88:89], v[152:153]
	s_waitcnt lgkmcnt(0)
	v_add_f32_e32 v160, v96, v97
	ds_bpermute_b32 v161, v195, v160
	v_lshlrev_b64 v[96:97], 11, v[228:229]
	v_lshl_add_u64 v[96:97], v[96:97], 0, v[222:223]
	v_lshl_add_u64 v[102:103], v[96:97], 2, s[92:93]
	v_lshl_add_u64 v[100:101], v[96:97], 1, s[98:99]
	v_pk_mul_f32 v[98:99], v[78:79], v[94:95]
	v_pk_mul_f32 v[96:97], v[76:77], v[92:93]
	s_and_b64 vcc, exec, s[6:7]
	global_store_dwordx4 v[102:103], v[92:95], off nt
	global_store_dwordx4 v[102:103], v[88:91], off offset:16 nt
	v_pk_mul_f32 v[104:105], v[74:75], v[90:91]
	v_pk_mul_f32 v[106:107], v[72:73], v[88:89]
	v_cvt_pk_bf16_f32 v96, v96, v97
	v_cvt_pk_bf16_f32 v97, v98, v99
	s_nop 0
	v_cvt_pk_bf16_f32 v98, v106, v107
	v_cvt_pk_bf16_f32 v99, v104, v105
	s_cbranch_vccnz .LBB0_332
	global_store_dwordx4 v[100:101], v[96:99], off
.LBB0_332:
	s_waitcnt vmcnt(14)
	v_pk_add_f32 v[86:87], v[86:87], v[150:151]
	v_pk_add_f32 v[84:85], v[84:85], v[148:149]
	v_pk_add_f32 v[82:83], v[82:83], v[146:147]
	v_pk_add_f32 v[80:81], v[80:81], v[144:145]
	v_pk_mul_f32 v[98:99], v[70:71], v[86:87]
	v_pk_mul_f32 v[96:97], v[68:69], v[84:85]
	s_and_b64 vcc, exec, s[6:7]
	global_store_dwordx4 v[102:103], v[84:87], off offset:512 nt
	global_store_dwordx4 v[102:103], v[80:83], off offset:528 nt
	v_pk_mul_f32 v[102:103], v[66:67], v[82:83]
	v_pk_mul_f32 v[104:105], v[64:65], v[80:81]
	v_cvt_pk_bf16_f32 v96, v96, v97
	v_cvt_pk_bf16_f32 v97, v98, v99
	s_nop 0
	v_cvt_pk_bf16_f32 v98, v104, v105
	v_cvt_pk_bf16_f32 v99, v102, v103
	s_cbranch_vccnz .LBB0_334
	global_store_dwordx4 v[100:101], v[96:99], off offset:256

;     __device__ __forceinline__ void operator()(const f32x4 (&acc)[2][2][4][2], const Unit& u, int wr, int wc, int fr, int fq) const {
;     ...
;         for (int bj = 0; bj < 2; ++bj) { gv[bj][0] = *(const f32x4*)(g + col0 + bj * HALF); gv[bj][1] = *(const f32x4*)(g + col0 + bj * HALF + 4); }
; #pragma unroll
;         for (int ai = 0; ai < 2; ++ai) {
;             f32x4 pre[4][2][2]; float rq[4];
; #pragma unroll
;             for (int m = 0; m < 4; ++m) { const size_t off = (size_t)(ai * HALF + wr * 64 + m * 16 + fr) * 2048 + col0; rq[m] = rs2 ? rs2[rt + ai * HALF + wr * 64 + m * 16 + fr] : 0.f;
; #pragma unroll
;                 for (int bj = 0; bj < 2; ++bj) { pre[m][bj][0] = *(const f32x4*)(bb + off + bj * HALF); pre[m][bj][1] = *(const f32x4*)(bb + off + bj * HALF + 4); } }
;             asm volatile("" ::: "memory");
; #pragma unroll
;             for (int m = 0; m < 4; ++m) { const int rl = ai * HALF + wr * 64 + m * 16 + fr; const size_t off = (size_t)rl * 2048 + col0; float s = 0.f; const float sc = rs2 ? __builtin_amdgcn_rcpf(rq[m] * (1.f / 2048.f) + 1e-6f) : 1.f;
; #pragma unroll
;                 for (int bj = 0; bj < 2; ++bj) {
;                     const f32x4 v0 = pre[m][bj][0] + acc[ai][bj][m][0] * sc, v1 = pre[m][bj][1] + acc[ai][bj][m][1] * sc;
;                     __builtin_nontemporal_store(v0, (f32x4*)(oo + off + bj * HALF)); __builtin_nontemporal_store(v1, (f32x4*)(oo + off + bj * HALF + 4));
;                     s += (v0[0] * v0[0] + v0[1] * v0[1]) + (v0[2] * v0[2] + v0[3] * v0[3]) + (v1[0] * v1[0] + v1[1] * v1[1]) + (v1[2] * v1[2] + v1[3] * v1[3]);
.LBB0_500:
	s_lshl_b32 s34, s91, 8
	s_or_b32 s34, s34, s86
	v_lshl_add_u32 v222, v221, 3, s34
	v_add_u32_e32 v228, s98, v220
	v_ashrrev_i32_e32 v223, 31, v222
	v_add_u32_e32 v226, s92, v228
	v_lshlrev_b64 v[144:145], 2, v[222:223]
	v_ashrrev_i32_e32 v227, 31, v226
	v_lshl_add_u64 v[68:69], s[42:43], 0, v[144:145]
	v_lshl_add_u64 v[224:225], s[4:5], 0, v[144:145]
	v_ashrrev_i32_e32 v229, 31, v228
	v_lshl_add_u64 v[144:145], v[226:227], 2, s[96:97]
	global_load_dwordx4 v[72:75], v[68:69], off offset:16
	global_load_dwordx4 v[76:79], v[68:69], off
	global_load_dwordx4 v[64:67], v[68:69], off offset:528
	s_nop 0
	global_load_dwordx4 v[68:71], v[68:69], off offset:512
	v_add_u32_e32 v234, 16, v228
	global_load_dword v238, v[144:145], off
	v_lshlrev_b64 v[144:145], 13, v[228:229]
	v_lshl_add_u64 v[144:145], v[224:225], 0, v[144:145]
	global_load_dwordx4 v[200:203], v[144:145], off offset:16
	global_load_dwordx4 v[206:209], v[144:145], off
	global_load_dwordx4 v[192:195], v[144:145], off offset:528
	global_load_dwordx4 v[196:199], v[144:145], off offset:512
	v_add_u32_e32 v144, 16, v226
	v_ashrrev_i32_e32 v145, 31, v144
	v_ashrrev_i32_e32 v235, 31, v234
	v_lshl_add_u64 v[144:145], v[144:145], 2, s[96:97]
	global_load_dword v246, v[144:145], off
	v_lshlrev_b64 v[144:145], 13, v[234:235]
	v_lshl_add_u64 v[144:145], v[224:225], 0, v[144:145]
	global_load_dwordx4 v[184:187], v[144:145], off offset:16
	global_load_dwordx4 v[188:191], v[144:145], off
	global_load_dwordx4 v[176:179], v[144:145], off offset:528
	global_load_dwordx4 v[180:183], v[144:145], off offset:512
	v_add_u32_e32 v144, 32, v226
	v_add_u32_e32 v232, 32, v228
	v_ashrrev_i32_e32 v145, 31, v144
	v_ashrrev_i32_e32 v233, 31, v232
	v_lshl_add_u64 v[144:145], v[144:145], 2, s[96:97]
	global_load_dword v248, v[144:145], off
	v_lshlrev_b64 v[144:145], 13, v[232:233]
	v_lshl_add_u64 v[144:145], v[224:225], 0, v[144:145]
	global_load_dwordx4 v[168:171], v[144:145], off offset:16
	global_load_dwordx4 v[172:175], v[144:145], off
	global_load_dwordx4 v[160:163], v[144:145], off offset:528
	global_load_dwordx4 v[164:167], v[144:145], off offset:512
	v_add_u32_e32 v144, 48, v226
	v_add_u32_e32 v230, 48, v228
	v_ashrrev_i32_e32 v145, 31, v144
	v_ashrrev_i32_e32 v231, 31, v230
	v_lshl_add_u64 v[144:145], v[144:145], 2, s[96:97]
	global_load_dword v227, v[144:145], off
	v_lshlrev_b64 v[144:145], 13, v[230:231]
	v_lshl_add_u64 v[148:149], v[224:225], 0, v[144:145]
	global_load_dwordx4 v[152:155], v[148:149], off offset:16
	global_load_dwordx4 v[156:159], v[148:149], off
	global_load_dwordx4 v[144:147], v[148:149], off offset:528
	s_nop 0
	global_load_dwordx4 v[148:151], v[148:149], off offset:512
	v_lshlrev_b64 v[236:237], 11, v[228:229]
	s_lshl_b64 s[4:5], s[92:93], 13
	s_add_u32 s66, s28, s4
	s_addc_u32 s67, s29, s5
	s_lshl_b64 s[4:5], s[92:93], 12
	s_add_u32 s68, s18, s4
	v_lshl_add_u64 v[240:241], v[236:237], 0, v[222:223]
	s_addc_u32 s69, s19, s5
	v_lshl_add_u64 v[236:237], v[240:241], 2, s[66:67]
	s_and_b64 vcc, exec, s[94:95]
	v_lshl_add_u64 v[240:241], v[240:241], 1, s[68:69]
	s_waitcnt vmcnt(17)
	v_fmamk_f32 v229, v238, 0x3a000000, v239
	v_rcp_f32_e32 v238, v229
	s_nop 0
	v_pk_fma_f32 v[142:143], v[142:143], v[238:239], v[208:209] op_sel_hi:[1,0,1]
	v_pk_fma_f32 v[140:141], v[140:141], v[238:239], v[206:207] op_sel_hi:[1,0,1]
	v_pk_fma_f32 v[138:139], v[138:139], v[238:239], v[202:203] op_sel_hi:[1,0,1]
	v_pk_fma_f32 v[136:137], v[136:137], v[238:239], v[200:201] op_sel_hi:[1,0,1]
	v_pk_mul_f32 v[202:203], v[78:79], v[142:143]
	v_pk_mul_f32 v[200:201], v[76:77], v[140:141]
	global_store_dwordx4 v[236:237], v[140:143], off nt
	global_store_dwordx4 v[236:237], v[136:139], off offset:16 nt
	v_pk_mul_f32 v[206:207], v[74:75], v[138:139]
	v_pk_mul_f32 v[208:209], v[72:73], v[136:137]
	v_cvt_pk_bf16_f32 v200, v200, v201
	v_cvt_pk_bf16_f32 v201, v202, v203
	s_nop 0
	v_cvt_pk_bf16_f32 v202, v208, v209
	v_cvt_pk_bf16_f32 v203, v206, v207
	s_cbranch_vccz .LBB0_502
	global_store_dwordx4 v[240:241], v[200:203], off
.LBB0_502:
	v_mov_b32_e32 v239, v238
	s_nop 0
	v_mov_b32_e32 v200, v238
	v_mov_b32_e32 v201, v238
	s_waitcnt vmcnt(17)
	v_pk_fma_f32 v[134:135], v[134:135], v[200:201], v[198:199]
	v_pk_fma_f32 v[132:133], v[132:133], v[238:239], v[196:197]
	v_pk_fma_f32 v[130:131], v[130:131], v[200:201], v[194:195]
	v_pk_fma_f32 v[128:129], v[128:129], v[238:239], v[192:193]
	v_pk_mul_f32 v[194:195], v[70:71], v[134:135]
	v_pk_mul_f32 v[192:193], v[68:69], v[132:133]
	global_store_dwordx4 v[236:237], v[132:135], off offset:512 nt
	global_store_dwordx4 v[236:237], v[128:131], off offset:528 nt
	v_cvt_pk_bf16_f32 v192, v192, v193
	v_cvt_pk_bf16_f32 v193, v194, v195
	v_cndmask_b32_e64 v195, 0, 1, s[94:95]
	v_cmp_ne_u32_e64 s[4:5], 1, v195
	s_andn2_b64 vcc, exec, s[94:95]
	v_pk_mul_f32 v[196:197], v[66:67], v[130:131]
	v_pk_mul_f32 v[198:199], v[64:65], v[128:129]
	s_nop 0
	v_cvt_pk_bf16_f32 v194, v198, v199
	v_cvt_pk_bf16_f32 v195, v196, v197
	s_cbranch_vccnz .LBB0_504
	global_store_dwordx4 v[240:241], v[192:195], off offset:256
; __device__ __forceinline__ unsigned cvt_pk_bf16(float lo, float hi) { unsigned r; asm volatile("v_cvt_pk_bf16_f32 %0, %1, %2" : "=v"(r) : "v"(lo), "v"(hi)); return r; }
;     __device__ __forceinline__ void operator()(const f32x4 (&acc)[2][2][4][2], const Unit& u, int wr, int wc, int fr, int fq) const {
;     ...
;             for (int m = 0; m < 4; ++m) { const int rl = ai * HALF + wr * 64 + m * 16 + fr; const size_t off = (size_t)rl * 2048 + col0; float s = 0.f; const float sc = rs2 ? __builtin_amdgcn_rcpf(rq[m] * (1.f / 2048.f) + 1e-6f) : 1.f;
; #pragma unroll
;                 for (int bj = 0; bj < 2; ++bj) {
;                     const f32x4 v0 = pre[m][bj][0] + acc[ai][bj][m][0] * sc, v1 = pre[m][bj][1] + acc[ai][bj][m][1] * sc;
;                     __builtin_nontemporal_store(v0, (f32x4*)(oo + off + bj * HALF)); __builtin_nontemporal_store(v1, (f32x4*)(oo + off + bj * HALF + 4));
;                     s += (v0[0] * v0[0] + v0[1] * v0[1]) + (v0[2] * v0[2] + v0[3] * v0[3]) + (v1[0] * v1[0] + v1[1] * v1[1]) + (v1[2] * v1[2] + v1[3] * v1[3]);
;                     const f32x4 a = v0 * gv[bj][0], b = v1 * gv[bj][1];
;                     u32x4 w; w.x = cvt_pk_bf16(a[0], a[1]); w.y = cvt_pk_bf16(a[2], a[3]); w.z = cvt_pk_bf16(b[0], b[1]); w.w = cvt_pk_bf16(b[2], b[3]);
;                     if (xn) *(u32x4*)(xx + off + bj * HALF) = w; }
;                 s += __shfl_xor(s, 16); s += __shfl_xor(s, 32); sacc[ai][m] = s; }
.LBB0_504:
	v_mul_f32_e32 v133, v133, v133
	v_fmac_f32_e32 v133, v132, v132
	v_mul_f32_e32 v132, v135, v135
	v_mul_f32_e32 v141, v141, v141
	v_fmac_f32_e32 v132, v134, v134
	v_mul_f32_e32 v129, v129, v129
	v_fmac_f32_e32 v141, v140, v140
	v_mul_f32_e32 v140, v143, v143
	v_add_f32_e32 v132, v133, v132
	v_fmac_f32_e32 v129, v128, v128
	v_fmac_f32_e32 v140, v142, v142
	v_mul_f32_e32 v137, v137, v137
	v_add_f32_e32 v128, v129, v132
	v_mul_f32_e32 v129, v131, v131
	v_add_f32_e32 v140, v141, v140
	v_fmac_f32_e32 v137, v136, v136
	v_fmac_f32_e32 v129, v130, v130
	v_and_b32_e32 v130, 64, v247
	v_add_f32_e32 v136, v137, v140
	v_mul_f32_e32 v137, v139, v139
	v_add_f32_e32 v128, v129, v128
	v_xor_b32_e32 v129, 16, v247
	v_add_u32_e32 v130, 64, v130
	v_fmac_f32_e32 v137, v138, v138
	v_cmp_lt_i32_e32 vcc, v129, v130
	v_add_f32_e32 v136, v137, v136
	v_add_f32_e32 v128, v136, v128
	v_cndmask_b32_e32 v129, v247, v129, vcc
	v_lshlrev_b32_e32 v194, 2, v129
	ds_bpermute_b32 v129, v194, v128
	v_mov_b32_e32 v239, 0x358637bd
	s_waitcnt vmcnt(16)
	v_fmamk_f32 v131, v246, 0x3a000000, v239
	v_rcp_f32_e32 v136, v131
	s_waitcnt lgkmcnt(0)
	v_add_f32_e32 v192, v128, v129
	v_xor_b32_e32 v128, 32, v247
	v_cmp_lt_i32_e32 vcc, v128, v130
	v_pk_fma_f32 v[126:127], v[126:127], v[136:137], v[190:191] op_sel_hi:[1,0,1]
	v_pk_fma_f32 v[124:125], v[124:125], v[136:137], v[188:189] op_sel_hi:[1,0,1]
	v_cndmask_b32_e32 v128, v247, v128, vcc
	v_lshlrev_b32_e32 v195, 2, v128
	ds_bpermute_b32 v193, v195, v192
	v_lshlrev_b64 v[128:129], 11, v[234:235]
	v_lshl_add_u64 v[128:129], v[128:129], 0, v[222:223]
	v_lshl_add_u64 v[134:135], v[128:129], 2, s[66:67]
	v_lshl_add_u64 v[132:133], v[128:129], 1, s[68:69]
	v_pk_fma_f32 v[122:123], v[122:123], v[136:137], v[186:187] op_sel_hi:[1,0,1]
	v_pk_fma_f32 v[120:121], v[120:121], v[136:137], v[184:185] op_sel_hi:[1,0,1]
	v_pk_mul_f32 v[130:131], v[78:79], v[126:127]
	v_pk_mul_f32 v[128:129], v[76:77], v[124:125]
	s_and_b64 vcc, exec, s[4:5]
	global_store_dwordx4 v[134:135], v[124:127], off nt
	global_store_dwordx4 v[134:135], v[120:123], off offset:16 nt
	v_pk_mul_f32 v[138:139], v[74:75], v[122:123]
	v_pk_mul_f32 v[140:141], v[72:73], v[120:121]
	v_cvt_pk_bf16_f32 v128, v128, v129
	v_cvt_pk_bf16_f32 v129, v130, v131
	s_nop 0
	v_cvt_pk_bf16_f32 v130, v140, v141
	v_cvt_pk_bf16_f32 v131, v138, v139
	s_cbranch_vccnz .LBB0_506
	global_store_dwordx4 v[132:133], v[128:131], off
.LBB0_506:
	v_mov_b32_e32 v137, v136
	s_nop 0
	v_mov_b32_e32 v128, v136
	v_mov_b32_e32 v129, v136
	s_waitcnt vmcnt(16)
	v_pk_fma_f32 v[118:119], v[118:119], v[128:129], v[182:183]
	v_pk_fma_f32 v[116:117], v[116:117], v[136:137], v[180:181]
	v_pk_fma_f32 v[114:115], v[114:115], v[128:129], v[178:179]
	v_pk_fma_f32 v[112:113], v[112:113], v[136:137], v[176:177]
	v_pk_mul_f32 v[130:131], v[70:71], v[118:119]
	v_pk_mul_f32 v[128:129], v[68:69], v[116:117]
	s_and_b64 vcc, exec, s[4:5]
	global_store_dwordx4 v[134:135], v[116:119], off offset:512 nt
	global_store_dwordx4 v[134:135], v[112:115], off offset:528 nt
	v_pk_mul_f32 v[134:135], v[66:67], v[114:115]
	v_pk_mul_f32 v[136:137], v[64:65], v[112:113]
	v_cvt_pk_bf16_f32 v128, v128, v129
	v_cvt_pk_bf16_f32 v129, v130, v131
	s_nop 0
	v_cvt_pk_bf16_f32 v130, v136, v137
	v_cvt_pk_bf16_f32 v131, v134, v135
	s_cbranch_vccnz .LBB0_508
	global_store_dwordx4 v[132:133], v[128:131], off offset:256
.LBB0_508:
	v_mul_f32_e32 v125, v125, v125
	v_mul_f32_e32 v117, v117, v117
	v_fmac_f32_e32 v125, v124, v124
	v_mul_f32_e32 v124, v127, v127
	v_fmac_f32_e32 v117, v116, v116
	v_mul_f32_e32 v116, v119, v119
	v_fmac_f32_e32 v124, v126, v126
	v_mul_f32_e32 v121, v121, v121
	v_fmac_f32_e32 v116, v118, v118
	v_mul_f32_e32 v113, v113, v113
	v_add_f32_e32 v124, v125, v124
	v_fmac_f32_e32 v121, v120, v120
	v_add_f32_e32 v116, v117, v116
	v_fmac_f32_e32 v113, v112, v112
	v_add_f32_e32 v120, v121, v124
	v_mul_f32_e32 v121, v123, v123
	v_add_f32_e32 v112, v113, v116
	v_mul_f32_e32 v113, v115, v115
	v_fmac_f32_e32 v121, v122, v122
	v_fmac_f32_e32 v113, v114, v114
	v_add_f32_e32 v120, v121, v120
	v_add_f32_e32 v112, v113, v112
	v_add_f32_e32 v112, v120, v112
	ds_bpermute_b32 v113, v194, v112
	s_waitcnt vmcnt(15)
	v_fmamk_f32 v114, v248, 0x3a000000, v239
	v_rcp_f32_e32 v120, v114
	s_and_b64 vcc, exec, s[4:5]
	s_waitcnt lgkmcnt(0)
	v_add_f32_e32 v176, v112, v113
	ds_bpermute_b32 v177, v195, v176
	v_lshlrev_b64 v[112:113], 11, v[232:233]
	v_lshl_add_u64 v[112:113], v[112:113], 0, v[222:223]
	v_pk_fma_f32 v[110:111], v[110:111], v[120:121], v[174:175] op_sel_hi:[1,0,1]
	v_pk_fma_f32 v[108:109], v[108:109], v[120:121], v[172:173] op_sel_hi:[1,0,1]
	v_lshl_add_u64 v[118:119], v[112:113], 2, s[66:67]
	v_lshl_add_u64 v[116:117], v[112:113], 1, s[68:69]
	v_pk_fma_f32 v[106:107], v[106:107], v[120:121], v[170:171] op_sel_hi:[1,0,1]
	v_pk_fma_f32 v[104:105], v[104:105], v[120:121], v[168:169] op_sel_hi:[1,0,1]
	v_pk_mul_f32 v[114:115], v[78:79], v[110:111]
	v_pk_mul_f32 v[112:113], v[76:77], v[108:109]
	global_store_dwordx4 v[118:119], v[108:111], off nt
	global_store_dwordx4 v[118:119], v[104:107], off offset:16 nt
	v_pk_mul_f32 v[122:123], v[74:75], v[106:107]
	v_pk_mul_f32 v[124:125], v[72:73], v[104:105]
	v_cvt_pk_bf16_f32 v112, v112, v113
	v_cvt_pk_bf16_f32 v113, v114, v115
	s_nop 0
	v_cvt_pk_bf16_f32 v114, v124, v125
	v_cvt_pk_bf16_f32 v115, v122, v123
	s_cbranch_vccnz .LBB0_510
	global_store_dwordx4 v[116:117], v[112:115], off
; __device__ __forceinline__ unsigned cvt_pk_bf16(float lo, float hi) { unsigned r; asm volatile("v_cvt_pk_bf16_f32 %0, %1, %2" : "=v"(r) : "v"(lo), "v"(hi)); return r; }
;     __device__ __forceinline__ void operator()(const f32x4 (&acc)[2][2][4][2], const Unit& u, int wr, int wc, int fr, int fq) const {
;     ...
;             for (int m = 0; m < 4; ++m) { const int rl = ai * HALF + wr * 64 + m * 16 + fr; const size_t off = (size_t)rl * 2048 + col0; float s = 0.f; const float sc = rs2 ? __builtin_amdgcn_rcpf(rq[m] * (1.f / 2048.f) + 1e-6f) : 1.f;
; #pragma unroll
;                 for (int bj = 0; bj < 2; ++bj) {
;                     const f32x4 v0 = pre[m][bj][0] + acc[ai][bj][m][0] * sc, v1 = pre[m][bj][1] + acc[ai][bj][m][1] * sc;
;                     __builtin_nontemporal_store(v0, (f32x4*)(oo + off + bj * HALF)); __builtin_nontemporal_store(v1, (f32x4*)(oo + off + bj * HALF + 4));
;                     s += (v0[0] * v0[0] + v0[1] * v0[1]) + (v0[2] * v0[2] + v0[3] * v0[3]) + (v1[0] * v1[0] + v1[1] * v1[1]) + (v1[2] * v1[2] + v1[3] * v1[3]);
;                     const f32x4 a = v0 * gv[bj][0], b = v1 * gv[bj][1];
;                     u32x4 w; w.x = cvt_pk_bf16(a[0], a[1]); w.y = cvt_pk_bf16(a[2], a[3]); w.z = cvt_pk_bf16(b[0], b[1]); w.w = cvt_pk_bf16(b[2], b[3]);
;                     if (xn) *(u32x4*)(xx + off + bj * HALF) = w; }
;                 s += __shfl_xor(s, 16); s += __shfl_xor(s, 32); sacc[ai][m] = s; }
.LBB0_510:
	v_mov_b32_e32 v121, v120
	s_nop 0
	v_mov_b32_e32 v112, v120
	v_mov_b32_e32 v113, v120
	s_waitcnt vmcnt(15)
	v_pk_fma_f32 v[102:103], v[102:103], v[112:113], v[166:167]
	v_pk_fma_f32 v[100:101], v[100:101], v[120:121], v[164:165]
	v_pk_fma_f32 v[98:99], v[98:99], v[112:113], v[162:163]
	v_pk_fma_f32 v[96:97], v[96:97], v[120:121], v[160:161]
	v_pk_mul_f32 v[114:115], v[70:71], v[102:103]
	v_pk_mul_f32 v[112:113], v[68:69], v[100:101]
	s_and_b64 vcc, exec, s[4:5]
	global_store_dwordx4 v[118:119], v[100:103], off offset:512 nt
	global_store_dwordx4 v[118:119], v[96:99], off offset:528 nt
	v_pk_mul_f32 v[118:119], v[66:67], v[98:99]
	v_pk_mul_f32 v[120:121], v[64:65], v[96:97]
	v_cvt_pk_bf16_f32 v112, v112, v113
	v_cvt_pk_bf16_f32 v113, v114, v115
	s_nop 0
	v_cvt_pk_bf16_f32 v114, v120, v121
	v_cvt_pk_bf16_f32 v115, v118, v119
	s_cbranch_vccnz .LBB0_512
	global_store_dwordx4 v[116:117], v[112:115], off offset:256
.LBB0_512:
	v_mul_f32_e32 v109, v109, v109
	v_mul_f32_e32 v101, v101, v101
	v_fmac_f32_e32 v109, v108, v108
	v_mul_f32_e32 v108, v111, v111
	v_fmac_f32_e32 v101, v100, v100
	v_mul_f32_e32 v100, v103, v103
	v_fmac_f32_e32 v108, v110, v110
	v_mul_f32_e32 v105, v105, v105
	v_fmac_f32_e32 v100, v102, v102
	v_mul_f32_e32 v97, v97, v97
	v_add_f32_e32 v108, v109, v108
	v_fmac_f32_e32 v105, v104, v104
	v_add_f32_e32 v100, v101, v100
	v_fmac_f32_e32 v97, v96, v96
	v_add_f32_e32 v104, v105, v108
	v_mul_f32_e32 v105, v107, v107
	v_add_f32_e32 v96, v97, v100
	v_mul_f32_e32 v97, v99, v99
	v_fmac_f32_e32 v105, v106, v106
	v_fmac_f32_e32 v97, v98, v98
	v_add_f32_e32 v104, v105, v104
	v_add_f32_e32 v96, v97, v96
	v_add_f32_e32 v96, v104, v96
	ds_bpermute_b32 v97, v194, v96
	s_waitcnt vmcnt(14)
	v_fmamk_f32 v98, v227, 0x3a000000, v239
	v_rcp_f32_e32 v104, v98
	s_and_b64 vcc, exec, s[4:5]
	s_waitcnt lgkmcnt(0)
	v_add_f32_e32 v160, v96, v97
	ds_bpermute_b32 v161, v195, v160
	v_lshlrev_b64 v[96:97], 11, v[230:231]
	v_lshl_add_u64 v[96:97], v[96:97], 0, v[222:223]
	v_pk_fma_f32 v[94:95], v[94:95], v[104:105], v[158:159] op_sel_hi:[1,0,1]
	v_pk_fma_f32 v[92:93], v[92:93], v[104:105], v[156:157] op_sel_hi:[1,0,1]
	v_lshl_add_u64 v[102:103], v[96:97], 2, s[66:67]
	v_lshl_add_u64 v[100:101], v[96:97], 1, s[68:69]
	v_pk_fma_f32 v[90:91], v[90:91], v[104:105], v[154:155] op_sel_hi:[1,0,1]
	v_pk_fma_f32 v[88:89], v[88:89], v[104:105], v[152:153] op_sel_hi:[1,0,1]
	v_pk_mul_f32 v[98:99], v[78:79], v[94:95]
	v_pk_mul_f32 v[96:97], v[76:77], v[92:93]
	global_store_dwordx4 v[102:103], v[92:95], off nt
	global_store_dwordx4 v[102:103], v[88:91], off offset:16 nt
	v_pk_mul_f32 v[106:107], v[74:75], v[90:91]
	v_pk_mul_f32 v[108:109], v[72:73], v[88:89]
	v_cvt_pk_bf16_f32 v96, v96, v97
	v_cvt_pk_bf16_f32 v97, v98, v99
	s_nop 0
	v_cvt_pk_bf16_f32 v98, v108, v109
	v_cvt_pk_bf16_f32 v99, v106, v107
	s_cbranch_vccnz .LBB0_514
	global_store_dwordx4 v[100:101], v[96:99], off
.LBB0_514:
	v_mov_b32_e32 v105, v104
	s_nop 0
	v_mov_b32_e32 v96, v104
	v_mov_b32_e32 v97, v104
	s_waitcnt vmcnt(14)
	v_pk_fma_f32 v[86:87], v[86:87], v[96:97], v[150:151]
	v_pk_fma_f32 v[84:85], v[84:85], v[104:105], v[148:149]
	v_pk_fma_f32 v[82:83], v[82:83], v[96:97], v[146:147]
	v_pk_fma_f32 v[80:81], v[80:81], v[104:105], v[144:145]
	v_pk_mul_f32 v[98:99], v[70:71], v[86:87]
	v_pk_mul_f32 v[96:97], v[68:69], v[84:85]
	s_and_b64 vcc, exec, s[4:5]
	global_store_dwordx4 v[102:103], v[84:87], off offset:512 nt
	global_store_dwordx4 v[102:103], v[80:83], off offset:528 nt
	v_pk_mul_f32 v[102:103], v[66:67], v[82:83]
	v_pk_mul_f32 v[104:105], v[64:65], v[80:81]
	v_cvt_pk_bf16_f32 v96, v96, v97
	v_cvt_pk_bf16_f32 v97, v98, v99
	s_nop 0
	v_cvt_pk_bf16_f32 v98, v104, v105
	v_cvt_pk_bf16_f32 v99, v102, v103
	s_cbranch_vccnz .LBB0_516
	global_store_dwordx4 v[100:101], v[96:99], off offset:256
; __device__ __forceinline__ unsigned cvt_pk_bf16(float lo, float hi) { unsigned r; asm volatile("v_cvt_pk_bf16_f32 %0, %1, %2" : "=v"(r) : "v"(lo), "v"(hi)); return r; }
;     __device__ __forceinline__ void operator()(const f32x4 (&acc)[2][2][4][2], const Unit& u, int wr, int wc, int fr, int fq) const {
;     ...
;         for (int ai = 0; ai < 2; ++ai) {
;             f32x4 pre[4][2][2]; float rq[4];
; #pragma unroll
;             for (int m = 0; m < 4; ++m) { const size_t off = (size_t)(ai * HALF + wr * 64 + m * 16 + fr) * 2048 + col0; rq[m] = rs2 ? rs2[rt + ai * HALF + wr * 64 + m * 16 + fr] : 0.f;
; #pragma unroll
;                 for (int bj = 0; bj < 2; ++bj) { pre[m][bj][0] = *(const f32x4*)(bb + off + bj * HALF); pre[m][bj][1] = *(const f32x4*)(bb + off + bj * HALF + 4); } }
;             asm volatile("" ::: "memory");
; #pragma unroll
;             for (int m = 0; m < 4; ++m) { const int rl = ai * HALF + wr * 64 + m * 16 + fr; const size_t off = (size_t)rl * 2048 + col0; float s = 0.f; const float sc = rs2 ? __builtin_amdgcn_rcpf(rq[m] * (1.f / 2048.f) + 1e-6f) : 1.f;
; #pragma unroll
;                 for (int bj = 0; bj < 2; ++bj) {
;                     const f32x4 v0 = pre[m][bj][0] + acc[ai][bj][m][0] * sc, v1 = pre[m][bj][1] + acc[ai][bj][m][1] * sc;
;                     __builtin_nontemporal_store(v0, (f32x4*)(oo + off + bj * HALF)); __builtin_nontemporal_store(v1, (f32x4*)(oo + off + bj * HALF + 4));
;                     s += (v0[0] * v0[0] + v0[1] * v0[1]) + (v0[2] * v0[2] + v0[3] * v0[3]) + (v1[0] * v1[0] + v1[1] * v1[1]) + (v1[2] * v1[2] + v1[3] * v1[3]);
;                     const f32x4 a = v0 * gv[bj][0], b = v1 * gv[bj][1];
;                     u32x4 w; w.x = cvt_pk_bf16(a[0], a[1]); w.y = cvt_pk_bf16(a[2], a[3]); w.z = cvt_pk_bf16(b[0], b[1]); w.w = cvt_pk_bf16(b[2], b[3]);
;                     if (xn) *(u32x4*)(xx + off + bj * HALF) = w; }
;                 s += __shfl_xor(s, 16); s += __shfl_xor(s, 32); sacc[ai][m] = s; }
.LBB0_516:
	v_mul_f32_e32 v93, v93, v93
	v_mul_f32_e32 v85, v85, v85
	v_fmac_f32_e32 v93, v92, v92
	v_mul_f32_e32 v92, v95, v95
	v_fmac_f32_e32 v85, v84, v84
	v_mul_f32_e32 v84, v87, v87
	v_fmac_f32_e32 v92, v94, v94
	v_mul_f32_e32 v89, v89, v89
	v_fmac_f32_e32 v84, v86, v86
	v_mul_f32_e32 v81, v81, v81
	v_add_f32_e32 v92, v93, v92
	v_fmac_f32_e32 v89, v88, v88
	v_add_f32_e32 v84, v85, v84
	v_fmac_f32_e32 v81, v80, v80
	v_add_f32_e32 v88, v89, v92
	v_mul_f32_e32 v89, v91, v91
	v_add_f32_e32 v80, v81, v84
	v_mul_f32_e32 v81, v83, v83
	v_fmac_f32_e32 v89, v90, v90
	v_fmac_f32_e32 v81, v82, v82
	v_add_f32_e32 v88, v89, v88
	v_add_f32_e32 v80, v81, v80
	v_add_f32_e32 v80, v88, v80
	ds_bpermute_b32 v81, v194, v80
	v_add_u32_e32 v146, 0x80, v228
	v_ashrrev_i32_e32 v147, 31, v146
	v_add_u32_e32 v144, 0x90, v228
	s_waitcnt lgkmcnt(0)
	v_add_f32_e32 v152, v80, v81
	v_add_u32_e32 v80, 0x80, v226
	v_ashrrev_i32_e32 v81, 31, v80
	v_lshl_add_u64 v[80:81], v[80:81], 2, s[96:97]
	global_load_dword v157, v[80:81], off
	v_ashrrev_i32_e32 v145, 31, v144
	v_add_u32_e32 v142, 0xa0, v228
	v_ashrrev_i32_e32 v143, 31, v142
	v_add_u32_e32 v140, 0xb0, v228
	v_ashrrev_i32_e32 v141, 31, v140
	ds_bpermute_b32 v153, v195, v152
	s_and_b64 vcc, exec, s[4:5]
	v_lshlrev_b64 v[80:81], 13, v[146:147]
	v_lshl_add_u64 v[80:81], v[224:225], 0, v[80:81]
	global_load_dwordx4 v[136:139], v[80:81], off offset:16
	global_load_dwordx4 v[162:165], v[80:81], off
	global_load_dwordx4 v[128:131], v[80:81], off offset:528
	global_load_dwordx4 v[132:135], v[80:81], off offset:512
	v_add_u32_e32 v80, 0x90, v226
	v_ashrrev_i32_e32 v81, 31, v80
	v_lshl_add_u64 v[80:81], v[80:81], 2, s[96:97]
	global_load_dword v156, v[80:81], off
	v_lshlrev_b64 v[80:81], 13, v[144:145]
	v_lshl_add_u64 v[80:81], v[224:225], 0, v[80:81]
	global_load_dwordx4 v[120:123], v[80:81], off offset:16
	global_load_dwordx4 v[124:127], v[80:81], off
	global_load_dwordx4 v[112:115], v[80:81], off offset:528
	global_load_dwordx4 v[116:119], v[80:81], off offset:512
	v_add_u32_e32 v80, 0xa0, v226
	v_ashrrev_i32_e32 v81, 31, v80
	v_lshl_add_u64 v[80:81], v[80:81], 2, s[96:97]
	global_load_dword v155, v[80:81], off
	v_lshlrev_b64 v[80:81], 13, v[142:143]
	v_lshl_add_u64 v[80:81], v[224:225], 0, v[80:81]
	global_load_dwordx4 v[104:107], v[80:81], off offset:16
	global_load_dwordx4 v[108:111], v[80:81], off
	global_load_dwordx4 v[96:99], v[80:81], off offset:528
	global_load_dwordx4 v[100:103], v[80:81], off offset:512
	v_add_u32_e32 v80, 0xb0, v226
	v_ashrrev_i32_e32 v81, 31, v80
	v_lshl_add_u64 v[80:81], v[80:81], 2, s[96:97]
	global_load_dword v154, v[80:81], off
	v_lshlrev_b64 v[80:81], 13, v[140:141]
	v_lshl_add_u64 v[84:85], v[224:225], 0, v[80:81]
	global_load_dwordx4 v[88:91], v[84:85], off offset:16
	global_load_dwordx4 v[92:95], v[84:85], off
	global_load_dwordx4 v[80:83], v[84:85], off offset:528
	s_nop 0
	global_load_dwordx4 v[84:87], v[84:85], off offset:512
	s_waitcnt vmcnt(19)
	v_fmamk_f32 v148, v157, 0x3a000000, v239
	v_rcp_f32_e32 v148, v148
	v_lshlrev_b64 v[146:147], 11, v[146:147]
	v_lshl_add_u64 v[146:147], v[146:147], 0, v[222:223]
	v_lshl_add_u64 v[150:151], v[146:147], 2, s[66:67]
	v_lshl_add_u64 v[146:147], v[146:147], 1, s[68:69]
	s_waitcnt vmcnt(18)
	v_pk_fma_f32 v[58:59], v[58:59], v[148:149], v[138:139] op_sel_hi:[1,0,1]
	s_waitcnt vmcnt(17)
	v_pk_fma_f32 v[62:63], v[62:63], v[148:149], v[164:165] op_sel_hi:[1,0,1]
	v_pk_fma_f32 v[60:61], v[60:61], v[148:149], v[162:163] op_sel_hi:[1,0,1]
	v_pk_fma_f32 v[56:57], v[56:57], v[148:149], v[136:137] op_sel_hi:[1,0,1]
	v_pk_mul_f32 v[138:139], v[78:79], v[62:63]
	v_pk_mul_f32 v[136:137], v[76:77], v[60:61]
	global_store_dwordx4 v[150:151], v[60:63], off nt
	global_store_dwordx4 v[150:151], v[56:59], off offset:16 nt
	v_pk_mul_f32 v[158:159], v[74:75], v[58:59]
	v_pk_mul_f32 v[162:163], v[72:73], v[56:57]
	v_cvt_pk_bf16_f32 v136, v136, v137
	v_cvt_pk_bf16_f32 v137, v138, v139
	s_nop 0
	v_cvt_pk_bf16_f32 v138, v162, v163
	v_cvt_pk_bf16_f32 v139, v158, v159
	s_cbranch_vccnz .LBB0_518
	global_store_dwordx4 v[146:147], v[136:139], off
